# RES sample-path tail: batched partial-sum LDS reads and read-modify-write loads (one wait each)
# speedup vs baseline: 1.0005x; 1.0005x over previous
; __device__ __forceinline__ float bf2f(bfu h) { return __uint_as_float(((unsigned)h) << 16); }
; template <int EPI>
; __device__ __forceinline__ void gemm_phase(KP P, const bfu* __restrict__ A, const bfu* __restrict__ Bt, int K, int ntn, char* smem, const int wv) {
;     ...
;       __syncthreads();
; #pragma unroll
;       for (int rt = 0; rt < 2; ++rt)
; #pragma unroll
;         for (int ct = 0; ct < 4; ++ct) *(f32x4*)(sRed + ((wid * 8 + rt * 4 + ct) * 64 + lane) * 4) = pacc[rt][ct];
;       __syncthreads();
;       {
;         f32x4 sum = {0.f, 0.f, 0.f, 0.f};
; #pragma unroll
;         for (int ww = 0; ww < 8; ++ww) sum += *(const f32x4*)(sRed + ((ww * 8 + wid) * 64 + lane) * 4);
;         const int col = cb * 64 + (wid & 3) * 16 + fr;
; #pragma unroll
;         for (int j = 0; j < 4; ++j) {
;           const int srow = rb * 32 + (wid >> 2) * 16 + fq * 4 + j;
;           bfu* op = (bfu*)(P->ws + WS_XR) + (size_t)(MP + srow) * D + col;
;           if (EPI == EPI_OUTPROJ) {
;             const float rs = ssd_rstd((const float*)(P->ws + WS_SSQ), MP + srow);
;             *op = f2bf(P->in[1][(size_t)srow * D + col] + rs * sum[j]);
;           } else {
;             *op = f2bf(bf2f(*op) + sum[j]);
;           }
;         }
.Lsp_mm_done:
	v_lshl_add_u64 v[44:45], 64, 2, v[44:45]
	v_lshl_add_u64 v[46:47], 64, 2, v[46:47]
	v_lshl_add_u64 v[48:49], 64, 2, v[48:49]
	v_lshl_add_u64 v[50:51], 64, 2, v[50:51]
	v_lshl_add_u64 v[52:53], 64, 2, v[52:53]
	v_lshl_add_u64 v[54:55], 64, 2, v[54:55]
	s_add_i32 s18, s18, 0x80
	s_cmp_ge_u32 s18, s14
	s_cbranch_scc0 .LBB0_291
	s_waitcnt lgkmcnt(0)
	s_barrier
	ds_write_b128 v59, v[30:33]
	ds_write_b128 v59, v[26:29] offset:1024
	ds_write_b128 v59, v[22:25] offset:2048
	ds_write_b128 v59, v[18:21] offset:3072
	ds_write_b128 v59, v[14:17] offset:4096
	ds_write_b128 v59, v[10:13] offset:5120
	ds_write_b128 v59, v[6:9] offset:6144
	ds_write_b128 v59, v[2:5] offset:7168
	s_waitcnt lgkmcnt(0)
	s_barrier
	ds_read_b128 v[84:87], v60
	ds_read_b128 v[88:91], v60 offset:8192
	ds_read_b128 v[92:95], v60 offset:16384
	ds_read_b128 v[96:99], v60 offset:24576
	ds_read_b128 v[100:103], v60 offset:32768
	ds_read_b128 v[104:107], v60 offset:40960
	ds_read_b128 v[108:111], v60 offset:49152
	ds_read_b128 v[112:115], v60 offset:57344
	s_lshl_b32 s18, s9, 1
	s_andn2_b32 s18, s18, 31
	v_or_b32_e32 v0, s17, v56
	v_lshlrev_b32_e32 v0, 1, v0
	s_add_i32 s9, s9, s2
	s_add_i32 s8, s8, s16
	v_add_u32_e32 v6, s18, v57
	v_ashrrev_i32_e32 v7, 31, v6
	v_lshl_add_u64 v[8:9], s[4:5], 0, v[0:1]
	v_lshlrev_b64 v[10:11], 11, v[6:7]
	v_lshl_add_u64 v[10:11], v[8:9], 0, v[10:11]
	v_or_b32_e32 v12, 1, v6
	v_ashrrev_i32_e32 v13, 31, v12
	v_lshlrev_b64 v[12:13], 11, v[12:13]
	v_lshl_add_u64 v[12:13], v[8:9], 0, v[12:13]
	v_or_b32_e32 v14, 2, v6
	v_ashrrev_i32_e32 v15, 31, v14
	v_lshlrev_b64 v[14:15], 11, v[14:15]
	v_lshl_add_u64 v[14:15], v[8:9], 0, v[14:15]
	v_or_b32_e32 v16, 3, v6
	v_ashrrev_i32_e32 v17, 31, v16
	v_lshlrev_b64 v[16:17], 11, v[16:17]
	v_lshl_add_u64 v[16:17], v[8:9], 0, v[16:17]
	global_load_ushort v18, v[10:11], off
	global_load_ushort v19, v[12:13], off
	global_load_ushort v20, v[14:15], off
	global_load_ushort v21, v[16:17], off
	s_cmpk_gt_i32 s9, 0xff
	s_waitcnt lgkmcnt(0)
	v_pk_add_f32 v[22:23], v[86:87], 0 op_sel_hi:[1,0]
	v_pk_add_f32 v[24:25], v[84:85], 0 op_sel_hi:[1,0]
	v_pk_add_f32 v[22:23], v[22:23], v[90:91]
	v_pk_add_f32 v[24:25], v[24:25], v[88:89]
	v_pk_add_f32 v[22:23], v[22:23], v[94:95]
	v_pk_add_f32 v[24:25], v[24:25], v[92:93]
	v_pk_add_f32 v[22:23], v[22:23], v[98:99]
	v_pk_add_f32 v[24:25], v[24:25], v[96:97]
	v_pk_add_f32 v[22:23], v[22:23], v[102:103]
	v_pk_add_f32 v[24:25], v[24:25], v[100:101]
	v_pk_add_f32 v[22:23], v[22:23], v[106:107]
	v_pk_add_f32 v[24:25], v[24:25], v[104:105]
	v_pk_add_f32 v[22:23], v[22:23], v[110:111]
	v_pk_add_f32 v[24:25], v[24:25], v[108:109]
	v_pk_add_f32 v[22:23], v[22:23], v[114:115]
	v_pk_add_f32 v[24:25], v[24:25], v[112:113]
	s_waitcnt vmcnt(0)
	v_lshlrev_b32_e32 v18, 16, v18
	v_lshlrev_b32_e32 v19, 16, v19
	v_lshlrev_b32_e32 v20, 16, v20
	v_lshlrev_b32_e32 v21, 16, v21
	v_add_f32_e32 v18, v24, v18
	v_add_f32_e32 v19, v25, v19
	v_add_f32_e32 v20, v22, v20
	v_add_f32_e32 v21, v23, v21
	v_bfe_u32 v26, v18, 16, 1
	v_bfe_u32 v27, v19, 16, 1
	v_bfe_u32 v28, v20, 16, 1
	v_bfe_u32 v29, v21, 16, 1
	v_add3_u32 v18, v18, v26, s96
	v_add3_u32 v19, v19, v27, s96
	v_add3_u32 v20, v20, v28, s96
	v_add3_u32 v21, v21, v29, s96
	global_store_short_d16_hi v[10:11], v18, off
	global_store_short_d16_hi v[12:13], v19, off
	global_store_short_d16_hi v[14:15], v20, off
	global_store_short_d16_hi v[16:17], v21, off
	s_cbranch_scc0 .LBB0_290
